# diff-attn fast loop: softmax without running-max subtraction (C=0), per-unit finite/range check of l with full safe-mode (max-based) rerun fallback
# speedup vs baseline: 1.0563x; 1.0505x over previous
.LBB0_426:
	s_load_dwordx2 s[78:79], s[0:1], 0xb0
	s_cmpk_gt_i32 s33, 0x3ff
	s_waitcnt lgkmcnt(0)
	s_barrier
	s_cbranch_scc1 .LBB0_455
	v_add_f32_e32 v2, v131, v185
	v_add_f32_e32 v3, v184, v186
	v_mul_f32_e32 v2, 0x3fb8aa3b, v2
	v_mul_f32_e32 v3, 0x3fb8aa3b, v3
	v_readlane_b32 s2, v245, 0
	v_exp_f32_e32 v2, v2
	v_exp_f32_e32 v3, v3
	v_readlane_b32 s3, v245, 1
	s_load_dwordx2 s[16:17], s[2:3], 0x38
	s_lshl_b32 s46, s33, 2
	v_sub_f32_e32 v2, v2, v3
	v_add_f32_e32 v220, 0x3e4ccccd, v2
	s_lshl_b32 s47, s11, 2
	s_movk_i32 s48, 0x1500
	s_movk_i32 s49, 0x110
	v_mov_b32_e32 v3, 0
	s_add_i32 s50, 0, 0x10800
	s_mov_b64 s[18:19], 0xa800
	s_mov_b64 s[22:23], 0x800
	s_mov_b64 s[24:25], 0x880
	s_mov_b64 s[26:27], 0x1000
	s_mov_b64 s[28:29], 0x55000
	s_movk_i32 s51, 0x80
	s_movk_i32 s52, 0xc0
	s_mov_b64 s[30:31], 0xa9a8800
	s_mov_b64 s[34:35], 0xa9a8880
	s_mov_b64 s[36:37], 0xa9a9000
	s_mov_b64 s[38:39], 0xa9fd000
	s_mov_b32 s53, 0x41000000
	v_mov_b32_e32 v221, 0x358637bd
	s_mov_b32 s54, 0xf800000
	v_mov_b32_e32 v222, 0x260
	s_mov_b32 s68, 0
	v_mov_b32_e32 v2, 0x21800
	ds_write_b32 v2, v3
	s_branch .LBB0_429

.LBB0_433:
	v_and_b32_e32 v2, 31, v223
	v_ashrrev_i32_e32 v8, 5, v223
	v_lshrrev_b32_e32 v9, 1, v223
	v_lshlrev_b32_e32 v10, 7, v2
	v_bitop3_b32 v11, v9, v8, 7 bitop3:0x6c
	v_lshl_add_u32 v226, v11, 4, v10
	v_add_u32_e32 v11, 2, v8
	v_bitop3_b32 v11, v11, v9, 7 bitop3:0x78
	v_lshl_add_u32 v227, v11, 4, v10
	v_add_u32_e32 v11, 4, v8
	v_bitop3_b32 v11, v11, v9, 7 bitop3:0x78
	s_add_i32 s2, s3, 0
	v_lshl_add_u32 v228, v11, 4, v10
	v_add_u32_e32 v11, 6, v8
	s_add_i32 s2, s2, 0x10800
	v_bitop3_b32 v9, v11, v9, 7 bitop3:0x78
	v_lshl_add_u32 v230, v9, 4, v10
	v_mov_b32_e32 v9, s2
	s_and_b32 s2, s5, 0x3fffffc0
	s_lshl_b32 s2, s2, 2
	s_add_i32 s56, s2, 0
	s_lshl_b32 s2, s46, 1
	s_add_i32 s56, s56, 0x10000
	s_and_b32 s5, s2, 0x700
	s_add_u32 s5, s7, s5
	v_mad_u32_u24 v18, v2, s49, v9
	v_lshl_add_u32 v229, v2, 2, s56
	s_addc_u32 s7, s6, 0
	s_mul_i32 s6, s4, 0xa800
	v_mul_lo_u32 v2, v4, s48
	v_add_u32_e32 v2, s6, v2
	s_add_u32 s6, s12, s5
	v_or_b32_e32 v2, v2, v7
	s_addc_u32 s7, s13, s7
	v_lshlrev_b32_e32 v225, 4, v8
	v_bfe_u32 v9, v223, 2, 2
	v_lshlrev_b32_e32 v8, 10, v8
	v_lshlrev_b32_e32 v10, 5, v5
	v_lshlrev_b32_e32 v11, 3, v223
	v_lshl_add_u64 v[210:211], v[2:3], 1, s[6:7]
	s_mulk_i32 s4, 0x5400
	v_mul_lo_u32 v2, v5, s48
	v_lshl_or_b32 v8, v9, 8, v8
	v_and_b32_e32 v10, 32, v10
	v_and_b32_e32 v11, 24, v11
	v_add_u32_e32 v2, s4, v2
	v_or3_b32 v8, v8, v10, v11
	v_lshlrev_b32_e32 v9, 6, v9
	v_or_b32_e32 v2, v2, v6
	v_mov_b32_e32 v16, v3
	v_mov_b32_e32 v17, v3
	v_or_b32_e32 v231, v8, v9
	v_bitop3_b32 v232, v8, 64, v9 bitop3:0x36
	v_bitop3_b32 v233, v8, s51, v9 bitop3:0x36
	v_bitop3_b32 v234, v8, s52, v9 bitop3:0x36
	v_lshl_add_u64 v[212:213], v[2:3], 1, s[6:7]
	v_mov_b32_e32 v2, v3
	v_mov_b32_e32 v4, v3
	v_mov_b32_e32 v5, v3
	v_mov_b32_e32 v6, v3
	v_mov_b32_e32 v7, v3
	v_mov_b32_e32 v8, v3
	v_mov_b32_e32 v9, v3
	v_mov_b32_e32 v10, v3
	v_mov_b32_e32 v11, v3
	v_mov_b32_e32 v12, v3
	v_mov_b32_e32 v13, v3
	v_mov_b32_e32 v14, v3
	v_mov_b32_e32 v15, v3
	v_add_u32_e32 v236, v18, v225
	v_mov_b64_e32 v[96:97], v[16:17]
	v_mov_b64_e32 v[80:81], v[16:17]
	v_mov_b64_e32 v[48:49], v[16:17]
	v_mov_b64_e32 v[32:33], v[16:17]
	v_mov_b64_e32 v[144:145], v[16:17]
	v_mov_b64_e32 v[128:129], v[16:17]
	v_mov_b64_e32 v[112:113], v[16:17]
	v_mov_b64_e32 v[64:65], v[16:17]
	v_cmp_gt_u32_e64 s[2:3], 32, v223
	s_mov_b32 s57, 0
	v_mov_b32_e32 v235, 0
	s_mov_b64 s[42:43], 0
	v_mov_b64_e32 v[94:95], v[14:15]
	v_mov_b64_e32 v[92:93], v[12:13]
	v_mov_b64_e32 v[90:91], v[10:11]
	v_mov_b64_e32 v[88:89], v[8:9]
	v_mov_b64_e32 v[86:87], v[6:7]
	v_mov_b64_e32 v[84:85], v[4:5]
	v_mov_b64_e32 v[82:83], v[2:3]
	v_mov_b64_e32 v[78:79], v[14:15]
	v_mov_b64_e32 v[76:77], v[12:13]
	v_mov_b64_e32 v[74:75], v[10:11]
	v_mov_b64_e32 v[72:73], v[8:9]
	v_mov_b64_e32 v[70:71], v[6:7]
	v_mov_b64_e32 v[68:69], v[4:5]
	v_mov_b64_e32 v[66:67], v[2:3]
	v_mov_b64_e32 v[46:47], v[14:15]
	v_mov_b64_e32 v[44:45], v[12:13]
	v_mov_b64_e32 v[42:43], v[10:11]
	v_mov_b64_e32 v[40:41], v[8:9]
	v_mov_b64_e32 v[38:39], v[6:7]
	v_mov_b64_e32 v[36:37], v[4:5]
	v_mov_b64_e32 v[34:35], v[2:3]
	v_mov_b64_e32 v[30:31], v[14:15]
	v_mov_b64_e32 v[28:29], v[12:13]
	v_mov_b64_e32 v[26:27], v[10:11]
	v_mov_b64_e32 v[24:25], v[8:9]
	v_mov_b64_e32 v[22:23], v[6:7]
	v_mov_b64_e32 v[20:21], v[4:5]
	v_mov_b64_e32 v[18:19], v[2:3]
	v_mov_b64_e32 v[142:143], v[14:15]
	v_mov_b64_e32 v[140:141], v[12:13]
	v_mov_b64_e32 v[138:139], v[10:11]
	v_mov_b64_e32 v[136:137], v[8:9]
	v_mov_b64_e32 v[134:135], v[6:7]
	v_mov_b64_e32 v[132:133], v[4:5]
	v_mov_b64_e32 v[130:131], v[2:3]
	v_mov_b64_e32 v[126:127], v[14:15]
	v_mov_b64_e32 v[124:125], v[12:13]
	v_mov_b64_e32 v[122:123], v[10:11]
	v_mov_b64_e32 v[120:121], v[8:9]
	v_mov_b64_e32 v[118:119], v[6:7]
	v_mov_b64_e32 v[116:117], v[4:5]
	v_mov_b64_e32 v[114:115], v[2:3]
	v_mov_b64_e32 v[110:111], v[14:15]
	v_mov_b64_e32 v[108:109], v[12:13]
	v_mov_b64_e32 v[106:107], v[10:11]
	v_mov_b64_e32 v[104:105], v[8:9]
	v_mov_b64_e32 v[102:103], v[6:7]
	v_mov_b64_e32 v[100:101], v[4:5]
	v_mov_b64_e32 v[98:99], v[2:3]
	v_mov_b64_e32 v[62:63], v[14:15]
	v_mov_b64_e32 v[60:61], v[12:13]
	v_mov_b64_e32 v[58:59], v[10:11]
	v_mov_b64_e32 v[56:57], v[8:9]
	v_mov_b64_e32 v[54:55], v[6:7]
	v_mov_b64_e32 v[52:53], v[4:5]
	v_mov_b64_e32 v[50:51], v[2:3]
	v_mov_b32_e32 v4, 0
	v_mov_b32_e32 v5, v224
	s_cmp_lg_u32 s68, 0
	s_cbranch_scc1 .LBB0_435
	s_branch .LBB0_435_f

.LBB0_452:
	ds_read_b128 v[6:9], v2 offset:224
	ds_read_b128 v[10:13], v2 offset:192
	ds_read_b128 v[14:17], v2 offset:160
	ds_read_b128 v[238:241], v2 offset:128
	s_waitcnt lgkmcnt(0)
	v_pk_mul_f32 v[142:143], v[142:143], v[6:7]
	v_pk_mul_f32 v[138:139], v[138:139], v[10:11]
	v_pk_mul_f32 v[134:135], v[134:135], v[14:15]
	v_pk_mul_f32 v[144:145], v[144:145], v[8:9]
	v_pk_mul_f32 v[140:141], v[140:141], v[12:13]
	v_pk_mul_f32 v[136:137], v[136:137], v[16:17]
	v_pk_mul_f32 v[132:133], v[132:133], v[240:241]
	v_pk_mul_f32 v[130:131], v[130:131], v[238:239]
	v_pk_mul_f32 v[126:127], v[126:127], v[6:7]
	v_pk_mul_f32 v[122:123], v[122:123], v[10:11]
	v_pk_mul_f32 v[118:119], v[118:119], v[14:15]
	v_pk_mul_f32 v[128:129], v[128:129], v[8:9]
	v_pk_mul_f32 v[124:125], v[124:125], v[12:13]
	v_pk_mul_f32 v[120:121], v[120:121], v[16:17]
	v_pk_mul_f32 v[116:117], v[116:117], v[240:241]
	v_pk_mul_f32 v[114:115], v[114:115], v[238:239]
	v_pk_mul_f32 v[110:111], v[110:111], v[6:7]
	v_pk_mul_f32 v[106:107], v[106:107], v[10:11]
	v_pk_mul_f32 v[102:103], v[102:103], v[14:15]
	v_pk_mul_f32 v[112:113], v[112:113], v[8:9]
	v_pk_mul_f32 v[108:109], v[108:109], v[12:13]
	v_pk_mul_f32 v[104:105], v[104:105], v[16:17]
	v_pk_mul_f32 v[100:101], v[100:101], v[240:241]
	v_pk_mul_f32 v[98:99], v[98:99], v[238:239]
	v_pk_mul_f32 v[62:63], v[62:63], v[6:7]
	v_pk_mul_f32 v[58:59], v[58:59], v[10:11]
	v_pk_mul_f32 v[54:55], v[54:55], v[14:15]
	v_pk_mul_f32 v[64:65], v[64:65], v[8:9]
	v_pk_mul_f32 v[60:61], v[60:61], v[12:13]
	v_pk_mul_f32 v[56:57], v[56:57], v[16:17]
	v_pk_mul_f32 v[52:53], v[52:53], v[240:241]
	v_pk_mul_f32 v[50:51], v[50:51], v[238:239]
	s_branch .LBB0_434
.LBB0_435_f:
	s_waitcnt vmcnt(0)
	s_barrier
	s_cmp_eq_u32 s42, 0x5358000
	s_cbranch_scc1 .LBB0_437_f
	s_add_i32 s4, s57, 0x8000
	s_and_b32 s4, s4, 0x8000
	v_lshl_add_u64 v[6:7], v[210:211], 0, s[42:43]
	s_add_i32 s4, s55, s4
	v_lshl_add_u64 v[8:9], v[6:7], 0, s[30:31]
	s_mov_b32 m0, s4
	v_lshl_add_u64 v[6:7], v[6:7], 0, s[34:35]
	global_load_lds_dwordx4 v[8:9], off
	s_add_i32 m0, s4, 0x2000
	s_nop 0
	global_load_lds_dwordx4 v[6:7], off
	v_lshl_add_u64 v[6:7], v[212:213], 0, s[42:43]
	v_lshl_add_u64 v[8:9], v[6:7], 0, s[36:37]
	s_add_i32 m0, s4, 0x4000
	v_lshl_add_u64 v[6:7], v[6:7], 0, s[38:39]
	global_load_lds_dwordx4 v[8:9], off
	s_add_i32 m0, s4, 0x6000
	s_nop 0
	global_load_lds_dwordx4 v[6:7], off
.LBB0_437_f:
	s_and_b32 s4, s57, 0x8000
	s_add_i32 s58, s4, 0
	v_add_u32_e32 v237, s58, v226
	v_add_u32_e32 v242, s58, v227
	v_add_u32_e32 v243, s58, v228
	v_add_u32_e32 v244, s58, v230
	ds_read_b128 v[6:9], v236
	ds_read_b128 v[178:181], v237
	ds_read_b128 v[182:185], v237 offset:4096
	ds_read_b128 v[10:13], v236 offset:32
	ds_read_b128 v[186:189], v242
	ds_read_b128 v[190:193], v242 offset:4096
	ds_read_b128 v[14:17], v236 offset:64
	ds_read_b128 v[194:197], v243
	ds_read_b128 v[198:201], v243 offset:4096
	ds_read_b128 v[238:241], v236 offset:96
	ds_read_b128 v[202:205], v244
	ds_read_b128 v[206:209], v244 offset:4096
	s_waitcnt lgkmcnt(9)
	v_mfma_f32_32x32x16_bf16 v[162:177], v[178:181], v[6:9], 0
	v_mfma_f32_32x32x16_bf16 v[146:161], v[182:185], v[6:9], 0
	ds_read_b128 v[246:249], v236 offset:128
	ds_read_b128 v[250:253], v237 offset:8192
	ds_read_b128 v[6:9], v237 offset:12288
	s_waitcnt lgkmcnt(9)
	v_mfma_f32_32x32x16_bf16 v[162:177], v[186:189], v[10:13], v[162:177]
	v_mfma_f32_32x32x16_bf16 v[146:161], v[190:193], v[10:13], v[146:161]
	ds_read_b128 v[10:13], v236 offset:160
	s_waitcnt lgkmcnt(7)
	v_mfma_f32_32x32x16_bf16 v[162:177], v[194:197], v[14:17], v[162:177]
	v_mfma_f32_32x32x16_bf16 v[146:161], v[198:201], v[14:17], v[146:161]
	ds_read_b128 v[14:17], v242 offset:8192
	s_waitcnt lgkmcnt(5)
	v_mfma_f32_32x32x16_bf16 v[162:177], v[202:205], v[238:241], v[162:177]
	v_mfma_f32_32x32x16_bf16 v[146:161], v[206:209], v[238:241], v[146:161]
	ds_read_b128 v[238:241], v242 offset:12288
	s_waitcnt lgkmcnt(3)
	v_mfma_f32_32x32x16_bf16 v[194:209], v[250:253], v[246:249], 0
	v_mfma_f32_32x32x16_bf16 v[178:193], v[6:9], v[246:249], 0
	ds_read_b128 v[246:249], v236 offset:192
	ds_read_b128 v[250:253], v243 offset:8192
	ds_read_b128 v[6:9], v243 offset:12288
	s_waitcnt lgkmcnt(3)
	v_mfma_f32_32x32x16_bf16 v[194:209], v[14:17], v[10:13], v[194:209]
	v_mfma_f32_32x32x16_bf16 v[178:193], v[238:241], v[10:13], v[178:193]
	ds_read_b128 v[10:13], v236 offset:224
	ds_read_b128 v[14:17], v244 offset:8192
	ds_read_b128 v[238:241], v244 offset:12288
	s_waitcnt lgkmcnt(3)
	v_mfma_f32_32x32x16_bf16 v[194:209], v[250:253], v[246:249], v[194:209]
	v_mfma_f32_32x32x16_bf16 v[178:193], v[6:9], v[246:249], v[178:193]
	s_waitcnt lgkmcnt(0)
	v_mfma_f32_32x32x16_bf16 v[194:209], v[14:17], v[10:13], v[194:209]
	v_mfma_f32_32x32x16_bf16 v[178:193], v[238:241], v[10:13], v[178:193]
	v_exp_f32_e32 v166, v166
	v_exp_f32_e32 v167, v167
	v_exp_f32_e32 v168, v168
	v_exp_f32_e32 v169, v169
	s_nop 6
	v_exp_f32_e32 v2, v194
	v_exp_f32_e32 v194, v195
	v_exp_f32_e32 v195, v196
	v_exp_f32_e32 v196, v197
	v_exp_f32_e32 v197, v198
	v_exp_f32_e32 v198, v199
	v_exp_f32_e32 v199, v200
	v_exp_f32_e32 v200, v201
	v_exp_f32_e32 v201, v162
	v_exp_f32_e32 v237, v163
	v_exp_f32_e32 v238, v164
	v_exp_f32_e32 v239, v165
	v_add_u32_e32 v240, s58, v231
	v_add_u32_e32 v241, s58, v232
	v_cvt_pk_bf16_f32 v6, v201, v237
	v_cvt_pk_bf16_f32 v7, v238, v239
	v_cvt_pk_bf16_f32 v8, v166, v167
	v_cvt_pk_bf16_f32 v9, v168, v169
	ds_read_b64_tr_b16 v[10:11], v240 offset:16384
	ds_read_b64_tr_b16 v[12:13], v240 offset:18432
	v_cvt_pk_bf16_f32 v14, v2, v194
	ds_read_b64_tr_b16 v[162:163], v241 offset:16384
	ds_read_b64_tr_b16 v[164:165], v241 offset:18432
	v_cvt_pk_bf16_f32 v15, v195, v196
	v_cvt_pk_bf16_f32 v16, v197, v198
	v_cvt_pk_bf16_f32 v17, v199, v200
	v_add_u32_e32 v242, s58, v233
	v_add_u32_e32 v243, s58, v234
	s_waitcnt lgkmcnt(2)
	v_mfma_f32_32x32x16_bf16 v[82:97], v[6:9], v[10:13], v[82:97]
	v_exp_f32_e32 v202, v202
	v_exp_f32_e32 v203, v203
	v_exp_f32_e32 v204, v204
	v_exp_f32_e32 v205, v205
	v_exp_f32_e32 v206, v206
	v_exp_f32_e32 v207, v207
	v_exp_f32_e32 v208, v208
	v_mfma_f32_32x32x16_bf16 v[130:145], v[14:17], v[10:13], v[130:145]
	ds_read_b64_tr_b16 v[10:11], v242 offset:16384
	ds_read_b64_tr_b16 v[12:13], v242 offset:18432
	v_exp_f32_e32 v170, v170
	v_exp_f32_e32 v171, v171
	v_exp_f32_e32 v172, v172
	v_exp_f32_e32 v173, v173
	v_exp_f32_e32 v174, v174
	v_exp_f32_e32 v175, v175
	s_waitcnt lgkmcnt(2)
	v_mfma_f32_32x32x16_bf16 v[66:81], v[6:9], v[162:165], v[66:81]
	v_exp_f32_e32 v176, v176
	v_exp_f32_e32 v177, v177
	v_exp_f32_e32 v209, v209
	v_exp_f32_e32 v178, v178
	v_exp_f32_e32 v179, v179
	v_exp_f32_e32 v180, v180
	v_exp_f32_e32 v181, v181
	v_mfma_f32_32x32x16_bf16 v[114:129], v[14:17], v[162:165], v[114:129]
	ds_read_b64_tr_b16 v[162:163], v243 offset:16384
	ds_read_b64_tr_b16 v[164:165], v243 offset:18432
	v_add_f32_e32 v2, v178, v2
	v_add_f32_e32 v2, 0, v2
	v_add_f32_e32 v194, v179, v194
	v_add_f32_e32 v2, v194, v2
	v_add_f32_e32 v194, v180, v195
	s_waitcnt lgkmcnt(2)
	v_mfma_f32_32x32x16_bf16 v[34:49], v[6:9], v[10:13], v[34:49]
	v_add_f32_e32 v2, v194, v2
	v_add_f32_e32 v194, v181, v196
	v_add_f32_e32 v2, v194, v2
	v_exp_f32_e32 v182, v182
	v_exp_f32_e32 v183, v183
	v_exp_f32_e32 v184, v184
	v_exp_f32_e32 v194, v146
	v_mfma_f32_32x32x16_bf16 v[98:113], v[14:17], v[10:13], v[98:113]
	ds_read_b64_tr_b16 v[10:11], v240 offset:20480
	ds_read_b64_tr_b16 v[12:13], v240 offset:22528
	v_exp_f32_e32 v195, v147
	v_exp_f32_e32 v196, v148
	v_exp_f32_e32 v244, v149
	v_exp_f32_e32 v150, v150
	v_exp_f32_e32 v151, v151
	v_exp_f32_e32 v152, v152
	s_waitcnt lgkmcnt(2)
	v_mfma_f32_32x32x16_bf16 v[18:33], v[6:9], v[162:165], v[18:33]
	v_cvt_pk_bf16_f32 v6, v170, v171
	v_cvt_pk_bf16_f32 v7, v172, v173
	v_cvt_pk_bf16_f32 v8, v174, v175
	v_cvt_pk_bf16_f32 v9, v176, v177
	v_exp_f32_e32 v153, v153
	v_exp_f32_e32 v154, v154
	v_exp_f32_e32 v155, v155
	v_mfma_f32_32x32x16_bf16 v[50:65], v[14:17], v[162:165], v[50:65]
	v_cvt_pk_bf16_f32 v14, v202, v203
	ds_read_b64_tr_b16 v[162:163], v241 offset:20480
	ds_read_b64_tr_b16 v[164:165], v241 offset:22528
	v_cvt_pk_bf16_f32 v15, v204, v205
	v_cvt_pk_bf16_f32 v16, v206, v207
	v_cvt_pk_bf16_f32 v17, v208, v209
	v_exp_f32_e32 v156, v156
	s_waitcnt lgkmcnt(2)
	v_mfma_f32_32x32x16_bf16 v[82:97], v[6:9], v[10:13], v[82:97]
	v_exp_f32_e32 v157, v157
	v_exp_f32_e32 v158, v158
	v_exp_f32_e32 v159, v159
	v_exp_f32_e32 v160, v160
	v_exp_f32_e32 v161, v161
	s_add_u32 s42, s42, 0xa8000
	s_addc_u32 s43, s43, 0
	v_mfma_f32_32x32x16_bf16 v[130:145], v[14:17], v[10:13], v[130:145]
	ds_read_b64_tr_b16 v[10:11], v242 offset:20480
	ds_read_b64_tr_b16 v[12:13], v242 offset:22528
	s_add_i32 s57, s57, 0x8000
	s_cmp_eq_u32 s42, 0x5400000
	s_waitcnt lgkmcnt(2)
	v_mfma_f32_32x32x16_bf16 v[66:81], v[6:9], v[162:165], v[66:81]
	v_mfma_f32_32x32x16_bf16 v[114:129], v[14:17], v[162:165], v[114:129]
	ds_read_b64_tr_b16 v[162:163], v243 offset:20480
	ds_read_b64_tr_b16 v[164:165], v243 offset:22528
	s_waitcnt lgkmcnt(0)
	v_mfma_f32_32x32x16_bf16 v[18:33], v[6:9], v[162:165], v[18:33]
	v_mfma_f32_32x32x16_bf16 v[50:65], v[14:17], v[162:165], v[50:65]
	v_exp_f32_e32 v162, v185
	v_add_f32_e32 v163, v182, v197
	v_add_f32_e32 v2, v163, v2
	v_add_f32_e32 v163, v183, v198
	v_add_f32_e32 v2, v163, v2
	v_exp_f32_e32 v163, v186
	v_exp_f32_e32 v164, v188
	v_mfma_f32_32x32x16_bf16 v[34:49], v[6:9], v[10:13], v[34:49]
	v_cvt_pk_bf16_f32 v6, v194, v195
	v_cvt_pk_bf16_f32 v7, v196, v244
	v_cvt_pk_bf16_f32 v8, v150, v151
	v_cvt_pk_bf16_f32 v9, v152, v153
	v_exp_f32_e32 v165, v189
	v_mfma_f32_32x32x16_bf16 v[98:113], v[14:17], v[10:13], v[98:113]
	ds_read_b64_tr_b16 v[10:11], v240 offset:24576
	ds_read_b64_tr_b16 v[12:13], v240 offset:26624
	v_cvt_pk_bf16_f32 v14, v178, v179
	v_cvt_pk_bf16_f32 v15, v180, v181
	v_cvt_pk_bf16_f32 v16, v182, v183
	v_cvt_pk_bf16_f32 v17, v184, v162
	ds_read_b64_tr_b16 v[146:147], v241 offset:24576
	ds_read_b64_tr_b16 v[148:149], v241 offset:26624
	v_add_f32_e32 v178, v165, v205
	s_waitcnt lgkmcnt(2)
	v_mfma_f32_32x32x16_bf16 v[82:97], v[6:9], v[10:13], v[82:97]
	v_exp_f32_e32 v179, v190
	s_nop 0
	v_add_f32_e32 v180, v179, v206
	v_mfma_f32_32x32x16_bf16 v[130:145], v[14:17], v[10:13], v[130:145]
	v_add_f32_e32 v10, v184, v199
	v_add_f32_e32 v2, v10, v2
	v_add_f32_e32 v10, v162, v200
	v_exp_f32_e32 v162, v187
	v_add_f32_e32 v2, v10, v2
	v_add_f32_e32 v10, v163, v202
	v_add_f32_e32 v2, v10, v2
	v_add_f32_e32 v10, v162, v203
	v_add_f32_e32 v2, v10, v2
	v_add_f32_e32 v10, v164, v204
	v_add_f32_e32 v2, v10, v2
	v_add_f32_e32 v2, v178, v2
	v_exp_f32_e32 v178, v191
	ds_read_b64_tr_b16 v[10:11], v242 offset:24576
	ds_read_b64_tr_b16 v[12:13], v242 offset:26624
	s_waitcnt lgkmcnt(2)
	v_mfma_f32_32x32x16_bf16 v[66:81], v[6:9], v[146:149], v[66:81]
	v_add_f32_e32 v2, v180, v2
	v_exp_f32_e32 v180, v192
	v_add_f32_e32 v181, v178, v207
	v_add_f32_e32 v2, v181, v2
	v_exp_f32_e32 v181, v193
	v_mfma_f32_32x32x16_bf16 v[114:129], v[14:17], v[146:149], v[114:129]
	ds_read_b64_tr_b16 v[146:147], v243 offset:24576
	ds_read_b64_tr_b16 v[148:149], v243 offset:26624
	s_waitcnt lgkmcnt(2)
	v_mfma_f32_32x32x16_bf16 v[34:49], v[6:9], v[10:13], v[34:49]
	v_mfma_f32_32x32x16_bf16 v[98:113], v[14:17], v[10:13], v[98:113]
	v_add_f32_e32 v10, v180, v208
	v_add_f32_e32 v2, v10, v2
	ds_read_b64_tr_b16 v[10:11], v240 offset:28672
	ds_read_b64_tr_b16 v[12:13], v240 offset:30720
	s_waitcnt lgkmcnt(2)
	v_mfma_f32_32x32x16_bf16 v[18:33], v[6:9], v[146:149], v[18:33]
	v_cvt_pk_bf16_f32 v6, v154, v155
	v_cvt_pk_bf16_f32 v7, v156, v157
	v_cvt_pk_bf16_f32 v8, v158, v159
	v_cvt_pk_bf16_f32 v9, v160, v161
	v_mfma_f32_32x32x16_bf16 v[50:65], v[14:17], v[146:149], v[50:65]
	v_cvt_pk_bf16_f32 v14, v163, v162
	v_cvt_pk_bf16_f32 v15, v164, v165
	v_cvt_pk_bf16_f32 v16, v179, v178
	v_cvt_pk_bf16_f32 v17, v180, v181
	v_add_f32_e32 v162, v181, v209
	v_add_f32_e32 v2, v162, v2
	v_add_f32_e32 v4, v4, v2
	v_add_f32_e32 v2, v194, v201
	s_waitcnt lgkmcnt(0)
	v_mfma_f32_32x32x16_bf16 v[82:97], v[6:9], v[10:13], v[82:97]
	v_add_f32_e32 v2, 0, v2
	ds_read_b64_tr_b16 v[146:147], v241 offset:28672
	ds_read_b64_tr_b16 v[148:149], v241 offset:30720
	v_mfma_f32_32x32x16_bf16 v[130:145], v[14:17], v[10:13], v[130:145]
	v_add_f32_e32 v10, v195, v237
	v_add_f32_e32 v2, v10, v2
	v_add_f32_e32 v10, v196, v238
	v_add_f32_e32 v2, v10, v2
	v_add_f32_e32 v10, v244, v239
	v_add_f32_e32 v2, v10, v2
	v_add_f32_e32 v10, v150, v166
	v_add_f32_e32 v2, v10, v2
	v_add_f32_e32 v10, v151, v167
	v_add_f32_e32 v2, v10, v2
	v_add_f32_e32 v10, v152, v168
	s_waitcnt lgkmcnt(0)
	v_mfma_f32_32x32x16_bf16 v[66:81], v[6:9], v[146:149], v[66:81]
	v_add_f32_e32 v2, v10, v2
	ds_read_b64_tr_b16 v[10:11], v242 offset:28672
	ds_read_b64_tr_b16 v[12:13], v242 offset:30720
	v_add_f32_e32 v150, v153, v169
	v_add_f32_e32 v2, v150, v2
	v_add_f32_e32 v150, v154, v170
	v_add_f32_e32 v2, v150, v2
	v_add_f32_e32 v150, v155, v171
	v_mfma_f32_32x32x16_bf16 v[114:129], v[14:17], v[146:149], v[114:129]
	ds_read_b64_tr_b16 v[146:147], v243 offset:28672
	ds_read_b64_tr_b16 v[148:149], v243 offset:30720
	v_add_f32_e32 v2, v150, v2
	v_add_f32_e32 v150, v156, v172
	v_add_f32_e32 v2, v150, v2
	v_add_f32_e32 v150, v157, v173
	v_add_f32_e32 v2, v150, v2
	s_waitcnt lgkmcnt(2)
	v_mfma_f32_32x32x16_bf16 v[34:49], v[6:9], v[10:13], v[34:49]
	v_mfma_f32_32x32x16_bf16 v[98:113], v[14:17], v[10:13], v[98:113]
	v_add_f32_e32 v10, v158, v174
	v_add_f32_e32 v2, v10, v2
	v_add_f32_e32 v10, v159, v175
	v_add_f32_e32 v2, v10, v2
	v_add_f32_e32 v10, v160, v176
	v_add_f32_e32 v2, v10, v2
	v_add_f32_e32 v10, v161, v177
	s_waitcnt lgkmcnt(0)
	v_mfma_f32_32x32x16_bf16 v[18:33], v[6:9], v[146:149], v[18:33]
	v_add_f32_e32 v2, v10, v2
	v_add_f32_e32 v235, v235, v2
	v_mfma_f32_32x32x16_bf16 v[50:65], v[14:17], v[146:149], v[50:65]
	s_cbranch_scc1 .LBB0_453
	s_branch .LBB0_435_f
.LBB0_453:
	s_setprio 0
	v_mov_b32_e32 v2, v235
	v_mov_b32_e32 v5, v4
	s_nop 0
	v_permlane32_swap_b32_e32 v235, v2
	v_permlane32_swap_b32_e32 v4, v5
	s_cmp_lg_u32 s68, 0
	s_cbranch_scc1 .Lsafe_done
	v_add_f32_e32 v6, v235, v2
	v_add_f32_e32 v7, v4, v5
	s_mov_b32 s69, 0x1f800000
	s_mov_b32 s70, 0x71800000
	v_cmp_nge_f32_e64 s[4:5], v6, s69
	v_cmp_nle_f32_e64 s[6:7], v6, s70
	s_or_b64 s[4:5], s[4:5], s[6:7]
	v_cmp_nge_f32_e64 s[6:7], v7, s69
	s_or_b64 s[4:5], s[4:5], s[6:7]
	v_cmp_nle_f32_e64 s[6:7], v7, s70
	s_or_b64 s[4:5], s[4:5], s[6:7]
	s_cmp_eq_u64 s[4:5], 0
	s_cbranch_scc1 .Lflag_skip
	v_mov_b32_e32 v6, 0x21800
	v_mov_b32_e32 v7, 1
	ds_write_b32 v6, v7
.Lflag_skip:
	s_waitcnt lgkmcnt(0)
	s_barrier
	v_mov_b32_e32 v6, 0x21800
	ds_read_b32 v7, v6
	s_waitcnt lgkmcnt(0)
	s_barrier
	v_readfirstlane_b32 s4, v7
	s_cmp_eq_u32 s4, 0
	s_cbranch_scc1 .Lcheck_done
	v_mov_b32_e32 v7, 0
	ds_write_b32 v6, v7
	s_mov_b32 s68, 1
	s_branch .LBB0_429
.Lsafe_done:
	s_mov_b32 s68, 0
.Lcheck_done:
	s_and_saveexec_b64 s[4:5], s[2:3]
	s_cbranch_execz .LBB0_428
	v_add_f32_e32 v4, v4, v5
	v_add_f32_e32 v2, v235, v2
	v_rcp_f32_e32 v4, v4
	v_rcp_f32_e32 v2, v2
	v_lshl_add_u32 v5, v223, 2, s56
	v_mul_f32_e32 v4, v220, v4
	ds_write_b32 v229, v2
	ds_write_b32 v5, v4 offset:128
	s_branch .LBB0_428
